# G2 out/h stores: agent-scope write-through (sc1) instead of system scope (sc0 sc1)
# baseline (speedup 1.0000x reference)
.LBB0_133:
	ds_read_b128 v[178:181], v130
	ds_read_b128 v[182:185], v130 offset:32
	ds_read_b128 v[186:189], v130 offset:4608
	ds_read_b128 v[190:193], v130 offset:4640
	ds_read_b128 v[194:197], v131 offset:36864
	ds_read_b128 v[198:201], v131 offset:36896
	ds_read_b128 v[202:205], v131 offset:41472
	ds_read_b128 v[206:209], v131 offset:41504
	s_waitcnt vmcnt(15)
	ds_write_b128 v139, v[94:97] offset:18432
	buffer_load_dwordx4 v[94:97], v140, s[40:43], s0 offen
	s_waitcnt lgkmcnt(4)
	v_mfma_f32_32x32x16_bf16 v[50:65], v[178:181], v[194:197], v[50:65]
	s_add_u32 s24, s44, s0
	s_addc_u32 s25, vcc_lo, s1
	s_and_b32 s25, s25, 0xffff
	s_waitcnt lgkmcnt(2)
	v_mfma_f32_32x32x16_bf16 v[34:49], v[178:181], v[202:205], v[34:49]
	s_waitcnt vmcnt(15)
	ds_write_b128 v139, v[90:93] offset:55296
	buffer_load_dwordx4 v[90:93], v140, s[24:27], 0 offen
	v_mfma_f32_32x32x16_bf16 v[18:33], v[186:189], v[194:197], v[18:33]
	v_mfma_f32_32x32x16_bf16 v[2:17], v[186:189], v[202:205], v[2:17]
	s_add_i32 s34, s0, 0x11000
	ds_read_b128 v[178:181], v130 offset:64
	ds_read_b128 v[186:189], v130 offset:4672
	ds_read_b128 v[194:197], v131 offset:36928
	ds_read_b128 v[202:205], v131 offset:41536
	s_waitcnt vmcnt(15)
	ds_write_b128 v139, v[86:89] offset:23040
	buffer_load_dwordx4 v[86:89], v140, s[40:43], s34 offen
	v_mfma_f32_32x32x16_bf16 v[50:65], v[182:185], v[198:201], v[50:65]
	s_waitcnt lgkmcnt(7)
	v_mfma_f32_32x32x16_bf16 v[34:49], v[182:185], v[206:209], v[34:49]
	s_waitcnt vmcnt(15)
	ds_write_b128 v139, v[82:85] offset:59904
	buffer_load_dwordx4 v[82:85], v140, s[24:27], s33 offen
	v_mfma_f32_32x32x16_bf16 v[18:33], v[190:193], v[198:201], v[18:33]
	v_mfma_f32_32x32x16_bf16 v[2:17], v[190:193], v[206:209], v[2:17]
	s_add_i32 s34, s0, 0x22000
	ds_read_b128 v[182:185], v130 offset:96
	ds_read_b128 v[190:193], v130 offset:4704
	ds_read_b128 v[198:201], v131 offset:36960
	ds_read_b128 v[206:209], v131 offset:41568
	s_waitcnt vmcnt(15)
	ds_write_b128 v139, v[78:81] offset:27648
	buffer_load_dwordx4 v[78:81], v140, s[40:43], s34 offen
	s_waitcnt lgkmcnt(8)
	v_mfma_f32_32x32x16_bf16 v[50:65], v[178:181], v[194:197], v[50:65]
	s_waitcnt lgkmcnt(7)
	v_mfma_f32_32x32x16_bf16 v[34:49], v[178:181], v[202:205], v[34:49]
	s_waitcnt vmcnt(15)
	ds_write_b128 v139, v[74:77] offset:64512
	buffer_load_dwordx4 v[74:77], v140, s[24:27], s29 offen
	v_mfma_f32_32x32x16_bf16 v[18:33], v[186:189], v[194:197], v[18:33]
	v_mfma_f32_32x32x16_bf16 v[2:17], v[186:189], v[202:205], v[2:17]
	s_add_i32 s34, s0, 0x33000
	s_waitcnt vmcnt(15)
	ds_write_b128 v139, v[70:73] offset:32256
	buffer_load_dwordx4 v[70:73], v140, s[40:43], s34 offen
	s_waitcnt lgkmcnt(4)
	v_mfma_f32_32x32x16_bf16 v[50:65], v[182:185], v[198:201], v[50:65]
	s_waitcnt lgkmcnt(3)
	v_mfma_f32_32x32x16_bf16 v[34:49], v[182:185], v[206:209], v[34:49]
	s_waitcnt vmcnt(15)
	ds_write_b128 v142, v[66:69] offset:13824
	buffer_load_dwordx4 v[66:69], v140, s[24:27], s3 offen
	v_mfma_f32_32x32x16_bf16 v[18:33], v[190:193], v[198:201], v[18:33]
	v_mfma_f32_32x32x16_bf16 v[2:17], v[190:193], v[206:209], v[2:17]
	s_min_u32 s24, vcc_hi, 11
	s_lshl_b32 s34, s24, 7
	s_add_i32 s24, s34, 0x200
	s_waitcnt lgkmcnt(0)
	s_barrier
	ds_read_b128 v[178:181], v130 offset:18432
	ds_read_b128 v[182:185], v130 offset:18464
	ds_read_b128 v[186:189], v130 offset:23040
	ds_read_b128 v[190:193], v130 offset:23072
	ds_read_b128 v[194:197], v131 offset:55296
	ds_read_b128 v[198:201], v131 offset:55328
	ds_read_b128 v[202:205], v131 offset:59904
	ds_read_b128 v[206:209], v131 offset:59936
	s_waitcnt vmcnt(15)
	ds_write_b128 v139, v[102:105]
	buffer_load_dwordx4 v[102:105], v140, s[40:43], s24 offen
	s_waitcnt lgkmcnt(4)
	v_mfma_f32_32x32x16_bf16 v[50:65], v[178:181], v[194:197], v[50:65]
	s_add_u32 s24, s44, s24
	s_addc_u32 s25, vcc_lo, 0
	s_and_b32 s25, s25, 0xffff
	s_waitcnt lgkmcnt(2)
	v_mfma_f32_32x32x16_bf16 v[34:49], v[178:181], v[202:205], v[34:49]
	s_waitcnt vmcnt(15)
	ds_write_b128 v139, v[98:101] offset:36864
	buffer_load_dwordx4 v[98:101], v140, s[24:27], 0 offen
	v_mfma_f32_32x32x16_bf16 v[18:33], v[186:189], v[194:197], v[18:33]
	v_mfma_f32_32x32x16_bf16 v[2:17], v[186:189], v[202:205], v[2:17]
	s_add_i32 s35, s34, 0x11200
	ds_read_b128 v[178:181], v130 offset:18496
	ds_read_b128 v[186:189], v130 offset:23104
	ds_read_b128 v[194:197], v131 offset:55360
	ds_read_b128 v[202:205], v131 offset:59968
	s_waitcnt vmcnt(15)
	ds_write_b128 v139, v[106:109] offset:4608
	buffer_load_dwordx4 v[106:109], v140, s[40:43], s35 offen
	v_mfma_f32_32x32x16_bf16 v[50:65], v[182:185], v[198:201], v[50:65]
	s_waitcnt lgkmcnt(7)
	v_mfma_f32_32x32x16_bf16 v[34:49], v[182:185], v[206:209], v[34:49]
	s_waitcnt vmcnt(15)
	ds_write_b128 v139, v[110:113] offset:41472
	buffer_load_dwordx4 v[110:113], v140, s[24:27], s33 offen
	v_mfma_f32_32x32x16_bf16 v[18:33], v[190:193], v[198:201], v[18:33]
	v_mfma_f32_32x32x16_bf16 v[2:17], v[190:193], v[206:209], v[2:17]
	s_add_i32 s35, s34, 0x22200
	ds_read_b128 v[182:185], v130 offset:18528
	ds_read_b128 v[190:193], v130 offset:23136
	ds_read_b128 v[198:201], v131 offset:55392
	ds_read_b128 v[206:209], v131 offset:60000
	s_waitcnt vmcnt(15)
	ds_write_b128 v139, v[114:117] offset:9216
	buffer_load_dwordx4 v[114:117], v140, s[40:43], s35 offen
	s_waitcnt lgkmcnt(8)
	v_mfma_f32_32x32x16_bf16 v[50:65], v[178:181], v[194:197], v[50:65]
	s_waitcnt lgkmcnt(7)
	v_mfma_f32_32x32x16_bf16 v[34:49], v[178:181], v[202:205], v[34:49]
	s_waitcnt vmcnt(15)
	ds_write_b128 v139, v[118:121] offset:46080
	buffer_load_dwordx4 v[118:121], v140, s[24:27], s29 offen
	v_mfma_f32_32x32x16_bf16 v[18:33], v[186:189], v[194:197], v[18:33]
	v_mfma_f32_32x32x16_bf16 v[2:17], v[186:189], v[202:205], v[2:17]
	s_add_i32 s34, s34, 0x33200
	s_waitcnt vmcnt(15)
	ds_write_b128 v139, v[122:125] offset:13824
	buffer_load_dwordx4 v[122:125], v140, s[40:43], s34 offen
	s_waitcnt lgkmcnt(4)
	v_mfma_f32_32x32x16_bf16 v[50:65], v[182:185], v[198:201], v[50:65]
	s_waitcnt lgkmcnt(3)
	v_mfma_f32_32x32x16_bf16 v[34:49], v[182:185], v[206:209], v[34:49]
	s_waitcnt vmcnt(15)
	ds_write_b128 v139, v[126:129] offset:50688
	buffer_load_dwordx4 v[126:129], v140, s[24:27], s3 offen
	v_mfma_f32_32x32x16_bf16 v[18:33], v[190:193], v[198:201], v[18:33]
	v_mfma_f32_32x32x16_bf16 v[2:17], v[190:193], v[206:209], v[2:17]
	s_add_i32 vcc_hi, vcc_hi, 2
	s_add_u32 s0, s0, 0x100
	s_addc_u32 s1, s1, 0
	s_cmp_lt_u32 vcc_hi, 14
	s_waitcnt lgkmcnt(0)
	s_barrier
	s_cbranch_scc1 .LBB0_133
	s_waitcnt vmcnt(6)
	ds_read_b128 v[98:101], v130
	ds_read_b128 v[102:105], v131 offset:36864
	s_waitcnt vmcnt(5)
	ds_read_b128 v[106:109], v130 offset:32
	s_waitcnt vmcnt(4)
	ds_read_b128 v[110:113], v131 offset:36896
	s_waitcnt vmcnt(3)
	ds_read_b128 v[114:117], v131 offset:41472
	s_waitcnt vmcnt(2)
	ds_read_b128 v[118:121], v130 offset:4608
	s_waitcnt vmcnt(1)
	ds_read_b128 v[122:125], v130 offset:4640
	s_waitcnt vmcnt(0)
	ds_read_b128 v[126:129], v131 offset:41504
	s_waitcnt lgkmcnt(3)
	v_mfma_f32_32x32x16_bf16 v[34:49], v[98:101], v[114:117], v[34:49]
	ds_write_b128 v139, v[94:97] offset:18432
	v_mfma_f32_32x32x16_bf16 v[50:65], v[98:101], v[102:105], v[50:65]
	s_waitcnt lgkmcnt(3)
	v_mfma_f32_32x32x16_bf16 v[18:33], v[118:121], v[102:105], v[18:33]
	ds_write_b128 v139, v[90:93] offset:55296
	v_mfma_f32_32x32x16_bf16 v[2:17], v[118:121], v[114:117], v[2:17]
	v_mfma_f32_32x32x16_bf16 v[50:65], v[106:109], v[110:113], v[50:65]
	ds_read_b128 v[90:93], v130 offset:64
	ds_read_b128 v[94:97], v130 offset:4672
	ds_read_b128 v[98:101], v131 offset:36928
	ds_read_b128 v[102:105], v131 offset:41536
	ds_write_b128 v139, v[86:89] offset:23040
	s_waitcnt lgkmcnt(7)
	v_mfma_f32_32x32x16_bf16 v[34:49], v[106:109], v[126:129], v[34:49]
	v_mfma_f32_32x32x16_bf16 v[18:33], v[122:125], v[110:113], v[18:33]
	ds_write_b128 v139, v[82:85] offset:59904
	v_mfma_f32_32x32x16_bf16 v[2:17], v[122:125], v[126:129], v[2:17]
	s_waitcnt lgkmcnt(3)
	v_mfma_f32_32x32x16_bf16 v[50:65], v[90:93], v[98:101], v[50:65]
	ds_read_b128 v[82:85], v130 offset:96
	ds_read_b128 v[86:89], v130 offset:4704
	ds_read_b128 v[106:109], v131 offset:36960
	ds_read_b128 v[110:113], v131 offset:41568
	ds_write_b128 v139, v[78:81] offset:27648
	s_waitcnt lgkmcnt(7)
	v_mfma_f32_32x32x16_bf16 v[34:49], v[90:93], v[102:105], v[34:49]
	v_mfma_f32_32x32x16_bf16 v[18:33], v[94:97], v[98:101], v[18:33]
	ds_write_b128 v139, v[74:77] offset:64512
	v_mfma_f32_32x32x16_bf16 v[2:17], v[94:97], v[102:105], v[2:17]
	s_waitcnt lgkmcnt(3)
	v_mfma_f32_32x32x16_bf16 v[50:65], v[82:85], v[106:109], v[50:65]
	ds_write_b128 v139, v[70:73] offset:32256
	s_waitcnt lgkmcnt(3)
	v_mfma_f32_32x32x16_bf16 v[34:49], v[82:85], v[110:113], v[34:49]
	v_mfma_f32_32x32x16_bf16 v[18:33], v[86:89], v[106:109], v[18:33]
	ds_write_b128 v142, v[66:69] offset:13824
	v_mfma_f32_32x32x16_bf16 v[2:17], v[86:89], v[110:113], v[2:17]
	s_waitcnt lgkmcnt(0)
	s_barrier
	ds_read_b128 v[66:69], v130 offset:18432
	ds_read_b128 v[70:73], v131 offset:55296
	ds_read_b128 v[74:77], v130 offset:18464
	ds_read_b128 v[78:81], v131 offset:55328
	ds_read_b128 v[82:85], v131 offset:59904
	ds_read_b128 v[86:89], v130 offset:23040
	ds_read_b128 v[90:93], v130 offset:23072
	ds_read_b128 v[94:97], v131 offset:59936
	s_waitcnt lgkmcnt(6)
	v_mfma_f32_32x32x16_bf16 v[50:65], v[66:69], v[70:73], v[50:65]
	s_waitcnt lgkmcnt(3)
	v_mfma_f32_32x32x16_bf16 v[34:49], v[66:69], v[82:85], v[34:49]
	s_waitcnt lgkmcnt(2)
	v_mfma_f32_32x32x16_bf16 v[18:33], v[86:89], v[70:73], v[18:33]
	v_mfma_f32_32x32x16_bf16 v[2:17], v[86:89], v[82:85], v[2:17]
	v_mfma_f32_32x32x16_bf16 v[50:65], v[74:77], v[78:81], v[50:65]
	ds_read_b128 v[66:69], v130 offset:18496
	ds_read_b128 v[70:73], v130 offset:23104
	ds_read_b128 v[82:85], v131 offset:55360
	ds_read_b128 v[86:89], v131 offset:59968
	s_waitcnt lgkmcnt(4)
	v_mfma_f32_32x32x16_bf16 v[34:49], v[74:77], v[94:97], v[34:49]
	v_mfma_f32_32x32x16_bf16 v[18:33], v[90:93], v[78:81], v[18:33]
	v_mfma_f32_32x32x16_bf16 v[2:17], v[90:93], v[94:97], v[2:17]
	s_waitcnt lgkmcnt(1)
	v_mfma_f32_32x32x16_bf16 v[50:65], v[66:69], v[82:85], v[50:65]
	ds_read_b128 v[74:77], v130 offset:18528
	ds_read_b128 v[78:81], v130 offset:23136
	ds_read_b128 v[90:93], v131 offset:55392
	ds_read_b128 v[94:97], v131 offset:60000
	s_waitcnt lgkmcnt(4)
	v_mfma_f32_32x32x16_bf16 v[34:49], v[66:69], v[86:89], v[34:49]
	v_mfma_f32_32x32x16_bf16 v[18:33], v[70:73], v[82:85], v[18:33]
	v_mfma_f32_32x32x16_bf16 v[2:17], v[70:73], v[86:89], v[2:17]
	s_waitcnt lgkmcnt(1)
	v_mfma_f32_32x32x16_bf16 v[50:65], v[74:77], v[90:93], v[50:65]
	s_waitcnt lgkmcnt(0)
	v_mfma_f32_32x32x16_bf16 v[34:49], v[74:77], v[94:97], v[34:49]
	v_mfma_f32_32x32x16_bf16 v[18:33], v[78:81], v[90:93], v[18:33]
	v_mfma_f32_32x32x16_bf16 v[2:17], v[78:81], v[94:97], v[2:17]
	v_lshrrev_b32_e32 v227, 5, v136
	s_lshl_b32 s0, s51, 9
	v_lshl_add_u32 v223, v227, 12, v222
	v_add_u32_e32 v223, s0, v223
	v_mov_b32_e32 v228, v223
	global_load_dwordx4 v[98:101], v228, s[68:69]
	v_add_u32_e32 v228, 0x8000, v228
	global_load_dwordx4 v[102:105], v228, s[68:69]
	v_add_u32_e32 v228, 0x8000, v228
	global_load_dwordx4 v[106:109], v228, s[68:69]
	v_add_u32_e32 v228, 0x8000, v228
	global_load_dwordx4 v[110:113], v228, s[68:69]
	v_add_u32_e32 v228, 0x8000, v228
	global_load_dwordx4 v[114:117], v228, s[68:69]
	v_add_u32_e32 v228, 0x8000, v228
	global_load_dwordx4 v[118:121], v228, s[68:69]
	v_add_u32_e32 v228, 0x8000, v228
	global_load_dwordx4 v[122:125], v228, s[68:69]
	v_add_u32_e32 v228, 0x8000, v228
	global_load_dwordx4 v[126:129], v228, s[68:69]
	v_add_u32_e32 v228, 0x8000, v228
	global_load_dwordx4 v[178:181], v228, s[68:69]
	v_add_u32_e32 v228, 0x8000, v228
	global_load_dwordx4 v[182:185], v228, s[68:69]
	v_add_u32_e32 v228, 0x8000, v228
	global_load_dwordx4 v[186:189], v228, s[68:69]
	v_add_u32_e32 v228, 0x8000, v228
	global_load_dwordx4 v[190:193], v228, s[68:69]
	v_add_u32_e32 v228, 0x8000, v228
	global_load_dwordx4 v[194:197], v228, s[68:69]
	v_add_u32_e32 v228, 0x8000, v228
	global_load_dwordx4 v[198:201], v228, s[68:69]
	v_add_u32_e32 v228, 0x8000, v228
	global_load_dwordx4 v[202:205], v228, s[68:69]
	v_add_u32_e32 v228, 0x8000, v228
	global_load_dwordx4 v[206:209], v228, s[68:69]
	v_lshl_or_b32 v66, v138, 2, v141
	s_movk_i32 s0, 0x210
	v_and_or_b32 v67, v136, 64, v137
	v_mul_lo_u32 v66, v66, s0
	v_lshl_add_u32 v66, v67, 2, v66
	s_barrier
	s_nop 3
	ds_write2_b32 v66, v50, v34 offset1:32
	ds_write2_b32 v66, v51, v35 offset0:132 offset1:164
	v_add_u32_e32 v34, 0x400, v66
	ds_write2_b32 v34, v52, v36 offset0:8 offset1:40
	ds_write2_b32 v34, v53, v37 offset0:140 offset1:172
	v_add_u32_e32 v34, 0x1000, v66
	ds_write2_b32 v34, v54, v38 offset0:32 offset1:64
	ds_write2_b32 v34, v55, v39 offset0:164 offset1:196
	v_add_u32_e32 v34, 0x1400, v66
	ds_write2_b32 v34, v56, v40 offset0:40 offset1:72
	ds_write2_b32 v34, v57, v41 offset0:172 offset1:204
	v_add_u32_e32 v34, 0x2000, v66
	ds_write2_b32 v34, v58, v42 offset0:64 offset1:96
	ds_write2_b32 v34, v59, v43 offset0:196 offset1:228
	v_add_u32_e32 v34, 0x2400, v66
	ds_write2_b32 v34, v60, v44 offset0:72 offset1:104
	ds_write2_b32 v34, v61, v45 offset0:204 offset1:236
	v_add_u32_e32 v34, 0x3000, v66
	ds_write2_b32 v34, v62, v46 offset0:96 offset1:128
	v_add_u32_e32 v34, 0x3200, v66
	ds_write2_b32 v34, v63, v47 offset0:100 offset1:132
	v_add_u32_e32 v34, 0x3400, v66
	ds_write2_b32 v34, v64, v48 offset0:104 offset1:136
	v_add_u32_e32 v34, 0x3600, v66
	ds_write2_b32 v34, v65, v49 offset0:108 offset1:140
	v_add_u32_e32 v34, 0x4000, v66
	ds_write2_b32 v34, v18, v2 offset0:128 offset1:160
	v_add_u32_e32 v2, 0x4400, v66
	ds_write2_b32 v2, v19, v3 offset0:4 offset1:36
	ds_write2_b32 v2, v20, v4 offset0:136 offset1:168
	v_add_u32_e32 v2, 0x4800, v66
	ds_write2_b32 v2, v21, v5 offset0:12 offset1:44
	v_add_u32_e32 v2, 0x5000, v66
	ds_write2_b32 v2, v22, v6 offset0:160 offset1:192
	v_add_u32_e32 v2, 0x5400, v66
	ds_write2_b32 v2, v23, v7 offset0:36 offset1:68
	ds_write2_b32 v2, v24, v8 offset0:168 offset1:200
	v_add_u32_e32 v2, 0x5800, v66
	ds_write2_b32 v2, v25, v9 offset0:44 offset1:76
	v_add_u32_e32 v2, 0x6000, v66
	ds_write2_b32 v2, v26, v10 offset0:192 offset1:224
	v_add_u32_e32 v2, 0x6400, v66
	ds_write2_b32 v2, v27, v11 offset0:68 offset1:100
	ds_write2_b32 v2, v28, v12 offset0:200 offset1:232
	v_add_u32_e32 v2, 0x6800, v66
	ds_write2_b32 v2, v29, v13 offset0:76 offset1:108
	v_add_u32_e32 v2, 0x7200, v66
	ds_write2_b32 v2, v30, v14 offset0:96 offset1:128
	v_add_u32_e32 v2, 0x7400, v66
	ds_write2_b32 v2, v31, v15 offset0:100 offset1:132
	v_add_u32_e32 v2, 0x7600, v66
	ds_write2_b32 v2, v32, v16 offset0:104 offset1:136
	v_add_u32_e32 v2, 0x7800, v66
	ds_write2_b32 v2, v33, v17 offset0:108 offset1:140
	s_waitcnt lgkmcnt(0)
	s_barrier
	v_lshrrev_b32_e32 v227, 5, v136
	v_mul_u32_u24_e32 v225, 0x210, v227
	v_add_u32_e32 v225, v225, v222
	ds_read_b128 v[2:5], v225
	ds_read_b128 v[6:9], v225 offset:4224
	ds_read_b128 v[10:13], v225 offset:8448
	ds_read_b128 v[14:17], v225 offset:12672
	ds_read_b128 v[18:21], v225 offset:16896
	ds_read_b128 v[22:25], v225 offset:21120
	ds_read_b128 v[26:29], v225 offset:25344
	ds_read_b128 v[30:33], v225 offset:29568
	ds_read_b128 v[34:37], v225 offset:33792
	ds_read_b128 v[38:41], v225 offset:38016
	ds_read_b128 v[42:45], v225 offset:42240
	ds_read_b128 v[46:49], v225 offset:46464
	ds_read_b128 v[50:53], v225 offset:50688
	ds_read_b128 v[54:57], v225 offset:54912
	ds_read_b128 v[58:61], v225 offset:59136
	ds_read_b128 v[62:65], v225 offset:63360
	v_mul_u32_u24_e32 v224, 0x880, v227
	s_lshl_b32 s0, s51, 8
	v_lshrrev_b32_e32 v228, 1, v222
	v_add3_u32 v224, v224, v228, s0
	v_lshlrev_b32_e32 v226, 2, v227
	s_waitcnt lgkmcnt(0)
	s_waitcnt vmcnt(15)
	v_pk_fma_f32 v[2:3], v[2:3], v[210:211], v[98:99]
	v_pk_fma_f32 v[4:5], v[4:5], v[212:213], v[100:101]
	s_waitcnt vmcnt(14)
	v_pk_fma_f32 v[6:7], v[6:7], v[210:211], v[102:103]
	v_pk_fma_f32 v[8:9], v[8:9], v[212:213], v[104:105]
	s_waitcnt vmcnt(13)
	v_pk_fma_f32 v[10:11], v[10:11], v[210:211], v[106:107]
	v_pk_fma_f32 v[12:13], v[12:13], v[212:213], v[108:109]
	s_waitcnt vmcnt(12)
	v_pk_fma_f32 v[14:15], v[14:15], v[210:211], v[110:111]
	v_pk_fma_f32 v[16:17], v[16:17], v[212:213], v[112:113]
	s_waitcnt vmcnt(11)
	v_pk_fma_f32 v[18:19], v[18:19], v[210:211], v[114:115]
	v_pk_fma_f32 v[20:21], v[20:21], v[212:213], v[116:117]
	s_waitcnt vmcnt(10)
	v_pk_fma_f32 v[22:23], v[22:23], v[210:211], v[118:119]
	v_pk_fma_f32 v[24:25], v[24:25], v[212:213], v[120:121]
	s_waitcnt vmcnt(9)
	v_pk_fma_f32 v[26:27], v[26:27], v[210:211], v[122:123]
	v_pk_fma_f32 v[28:29], v[28:29], v[212:213], v[124:125]
	s_waitcnt vmcnt(8)
	v_pk_fma_f32 v[30:31], v[30:31], v[210:211], v[126:127]
	v_pk_fma_f32 v[32:33], v[32:33], v[212:213], v[128:129]
	s_waitcnt vmcnt(7)
	v_pk_fma_f32 v[34:35], v[34:35], v[210:211], v[178:179]
	v_pk_fma_f32 v[36:37], v[36:37], v[212:213], v[180:181]
	s_waitcnt vmcnt(6)
	v_pk_fma_f32 v[38:39], v[38:39], v[210:211], v[182:183]
	v_pk_fma_f32 v[40:41], v[40:41], v[212:213], v[184:185]
	s_waitcnt vmcnt(5)
	v_pk_fma_f32 v[42:43], v[42:43], v[210:211], v[186:187]
	v_pk_fma_f32 v[44:45], v[44:45], v[212:213], v[188:189]
	s_waitcnt vmcnt(4)
	v_pk_fma_f32 v[46:47], v[46:47], v[210:211], v[190:191]
	v_pk_fma_f32 v[48:49], v[48:49], v[212:213], v[192:193]
	s_waitcnt vmcnt(3)
	v_pk_fma_f32 v[50:51], v[50:51], v[210:211], v[194:195]
	v_pk_fma_f32 v[52:53], v[52:53], v[212:213], v[196:197]
	s_waitcnt vmcnt(2)
	v_pk_fma_f32 v[54:55], v[54:55], v[210:211], v[198:199]
	v_pk_fma_f32 v[56:57], v[56:57], v[212:213], v[200:201]
	s_waitcnt vmcnt(1)
	v_pk_fma_f32 v[58:59], v[58:59], v[210:211], v[202:203]
	v_pk_fma_f32 v[60:61], v[60:61], v[212:213], v[204:205]
	s_waitcnt vmcnt(0)
	v_pk_fma_f32 v[62:63], v[62:63], v[210:211], v[206:207]
	v_pk_fma_f32 v[64:65], v[64:65], v[212:213], v[208:209]
	v_mov_b32_e32 v228, v223
	global_store_dwordx4 v228, v[2:5], s[70:71] sc1
	v_add_u32_e32 v228, 0x8000, v228
	global_store_dwordx4 v228, v[6:9], s[70:71] sc1
	v_add_u32_e32 v228, 0x8000, v228
	global_store_dwordx4 v228, v[10:13], s[70:71] sc1
	v_add_u32_e32 v228, 0x8000, v228
	global_store_dwordx4 v228, v[14:17], s[70:71] sc1
	v_add_u32_e32 v228, 0x8000, v228
	global_store_dwordx4 v228, v[18:21], s[70:71] sc1
	v_add_u32_e32 v228, 0x8000, v228
	global_store_dwordx4 v228, v[22:25], s[70:71] sc1
	v_add_u32_e32 v228, 0x8000, v228
	global_store_dwordx4 v228, v[26:29], s[70:71] sc1
	v_add_u32_e32 v228, 0x8000, v228
	global_store_dwordx4 v228, v[30:33], s[70:71] sc1
	v_add_u32_e32 v228, 0x8000, v228
	global_store_dwordx4 v228, v[34:37], s[70:71] sc1
	v_add_u32_e32 v228, 0x8000, v228
	global_store_dwordx4 v228, v[38:41], s[70:71] sc1
	v_add_u32_e32 v228, 0x8000, v228
	global_store_dwordx4 v228, v[42:45], s[70:71] sc1
	v_add_u32_e32 v228, 0x8000, v228
	global_store_dwordx4 v228, v[46:49], s[70:71] sc1
	v_add_u32_e32 v228, 0x8000, v228
	global_store_dwordx4 v228, v[50:53], s[70:71] sc1
	v_add_u32_e32 v228, 0x8000, v228
	global_store_dwordx4 v228, v[54:57], s[70:71] sc1
	v_add_u32_e32 v228, 0x8000, v228
	global_store_dwordx4 v228, v[58:61], s[70:71] sc1
	v_add_u32_e32 v228, 0x8000, v228
	global_store_dwordx4 v228, v[62:65], s[70:71] sc1
	s_cmp_lg_u64 s[54:55], 0
	s_cbranch_scc0 .LBB0_122
	v_pk_add_f32 v[218:219], v[218:219], 1.0 op_sel_hi:[1,0]
	v_pk_add_f32 v[220:221], v[220:221], 1.0 op_sel_hi:[1,0]
	v_pk_mul_f32 v[214:215], v[214:215], v[218:219]
	v_pk_mul_f32 v[216:217], v[216:217], v[220:221]
	v_pk_mul_f32 v[98:99], v[2:3], v[2:3]
	v_pk_mul_f32 v[100:101], v[4:5], v[4:5]
	v_pk_mul_f32 v[102:103], v[6:7], v[6:7]
	v_pk_mul_f32 v[104:105], v[8:9], v[8:9]
	v_pk_mul_f32 v[106:107], v[10:11], v[10:11]
	v_pk_mul_f32 v[108:109], v[12:13], v[12:13]
	v_pk_mul_f32 v[110:111], v[14:15], v[14:15]
	v_pk_mul_f32 v[112:113], v[16:17], v[16:17]
	v_pk_mul_f32 v[114:115], v[18:19], v[18:19]
	v_pk_mul_f32 v[116:117], v[20:21], v[20:21]
	v_pk_mul_f32 v[118:119], v[22:23], v[22:23]
	v_pk_mul_f32 v[120:121], v[24:25], v[24:25]
	v_pk_mul_f32 v[122:123], v[26:27], v[26:27]
	v_pk_mul_f32 v[124:125], v[28:29], v[28:29]
	v_pk_mul_f32 v[126:127], v[30:31], v[30:31]
	v_pk_mul_f32 v[128:129], v[32:33], v[32:33]
	v_pk_mul_f32 v[178:179], v[34:35], v[34:35]
	v_pk_mul_f32 v[180:181], v[36:37], v[36:37]
	v_pk_mul_f32 v[182:183], v[38:39], v[38:39]
	v_pk_mul_f32 v[184:185], v[40:41], v[40:41]
	v_pk_mul_f32 v[186:187], v[42:43], v[42:43]
	v_pk_mul_f32 v[188:189], v[44:45], v[44:45]
	v_pk_mul_f32 v[190:191], v[46:47], v[46:47]
	v_pk_mul_f32 v[192:193], v[48:49], v[48:49]
	v_pk_mul_f32 v[194:195], v[50:51], v[50:51]
	v_pk_mul_f32 v[196:197], v[52:53], v[52:53]
	v_pk_mul_f32 v[198:199], v[54:55], v[54:55]
	v_pk_mul_f32 v[200:201], v[56:57], v[56:57]
	v_pk_mul_f32 v[202:203], v[58:59], v[58:59]
	v_pk_mul_f32 v[204:205], v[60:61], v[60:61]
	v_pk_mul_f32 v[206:207], v[62:63], v[62:63]
	v_pk_mul_f32 v[208:209], v[64:65], v[64:65]
	v_add_f32_e32 v229, v98, v99
	v_add_f32_e32 v230, v102, v103
	v_add_f32_e32 v231, v106, v107
	v_add_f32_e32 v232, v110, v111
	v_add_f32_e32 v233, v114, v115
	v_add_f32_e32 v234, v118, v119
	v_add_f32_e32 v235, v122, v123
	v_add_f32_e32 v236, v126, v127
	v_add_f32_e32 v237, v178, v179
	v_add_f32_e32 v238, v182, v183
	v_add_f32_e32 v239, v186, v187
	v_add_f32_e32 v240, v190, v191
	v_add_f32_e32 v241, v194, v195
	v_add_f32_e32 v242, v198, v199
	v_add_f32_e32 v243, v202, v203
	v_add_f32_e32 v244, v206, v207
	v_add_f32_e32 v229, v229, v100
	v_add_f32_e32 v230, v230, v104
	v_add_f32_e32 v231, v231, v108
	v_add_f32_e32 v232, v232, v112
	v_add_f32_e32 v233, v233, v116
	v_add_f32_e32 v234, v234, v120
	v_add_f32_e32 v235, v235, v124
	v_add_f32_e32 v236, v236, v128
	v_add_f32_e32 v237, v237, v180
	v_add_f32_e32 v238, v238, v184
	v_add_f32_e32 v239, v239, v188
	v_add_f32_e32 v240, v240, v192
	v_add_f32_e32 v241, v241, v196
	v_add_f32_e32 v242, v242, v200
	v_add_f32_e32 v243, v243, v204
	v_add_f32_e32 v244, v244, v208
	v_add_f32_e32 v229, v229, v101
	v_add_f32_e32 v230, v230, v105
	v_add_f32_e32 v231, v231, v109
	v_add_f32_e32 v232, v232, v113
	v_add_f32_e32 v233, v233, v117
	v_add_f32_e32 v234, v234, v121
	v_add_f32_e32 v235, v235, v125
	v_add_f32_e32 v236, v236, v129
	v_add_f32_e32 v237, v237, v181
	v_add_f32_e32 v238, v238, v185
	v_add_f32_e32 v239, v239, v189
	v_add_f32_e32 v240, v240, v193
	v_add_f32_e32 v241, v241, v197
	v_add_f32_e32 v242, v242, v201
	v_add_f32_e32 v243, v243, v205
	v_add_f32_e32 v244, v244, v209
	v_pk_mul_f32 v[2:3], v[2:3], v[214:215]
	v_pk_mul_f32 v[4:5], v[4:5], v[216:217]
	v_pk_mul_f32 v[6:7], v[6:7], v[214:215]
	v_pk_mul_f32 v[8:9], v[8:9], v[216:217]
	v_pk_mul_f32 v[10:11], v[10:11], v[214:215]
	v_pk_mul_f32 v[12:13], v[12:13], v[216:217]
	v_pk_mul_f32 v[14:15], v[14:15], v[214:215]
	v_pk_mul_f32 v[16:17], v[16:17], v[216:217]
	v_pk_mul_f32 v[18:19], v[18:19], v[214:215]
	v_pk_mul_f32 v[20:21], v[20:21], v[216:217]
	v_pk_mul_f32 v[22:23], v[22:23], v[214:215]
	v_pk_mul_f32 v[24:25], v[24:25], v[216:217]
	v_pk_mul_f32 v[26:27], v[26:27], v[214:215]
	v_pk_mul_f32 v[28:29], v[28:29], v[216:217]
	v_pk_mul_f32 v[30:31], v[30:31], v[214:215]
	v_pk_mul_f32 v[32:33], v[32:33], v[216:217]
	v_pk_mul_f32 v[34:35], v[34:35], v[214:215]
	v_pk_mul_f32 v[36:37], v[36:37], v[216:217]
	v_pk_mul_f32 v[38:39], v[38:39], v[214:215]
	v_pk_mul_f32 v[40:41], v[40:41], v[216:217]
	v_pk_mul_f32 v[42:43], v[42:43], v[214:215]
	v_pk_mul_f32 v[44:45], v[44:45], v[216:217]
	v_pk_mul_f32 v[46:47], v[46:47], v[214:215]
	v_pk_mul_f32 v[48:49], v[48:49], v[216:217]
	v_pk_mul_f32 v[50:51], v[50:51], v[214:215]
	v_pk_mul_f32 v[52:53], v[52:53], v[216:217]
	v_pk_mul_f32 v[54:55], v[54:55], v[214:215]
	v_pk_mul_f32 v[56:57], v[56:57], v[216:217]
	v_pk_mul_f32 v[58:59], v[58:59], v[214:215]
	v_pk_mul_f32 v[60:61], v[60:61], v[216:217]
	v_pk_mul_f32 v[62:63], v[62:63], v[214:215]
	v_pk_mul_f32 v[64:65], v[64:65], v[216:217]
	v_cvt_pk_bf16_f32 v98, v2, v3
	v_cvt_pk_bf16_f32 v99, v4, v5
	v_cvt_pk_bf16_f32 v102, v6, v7
	v_cvt_pk_bf16_f32 v103, v8, v9
	v_cvt_pk_bf16_f32 v106, v10, v11
	v_cvt_pk_bf16_f32 v107, v12, v13
	v_cvt_pk_bf16_f32 v110, v14, v15
	v_cvt_pk_bf16_f32 v111, v16, v17
	v_cvt_pk_bf16_f32 v114, v18, v19
	v_cvt_pk_bf16_f32 v115, v20, v21
	v_cvt_pk_bf16_f32 v118, v22, v23
	v_cvt_pk_bf16_f32 v119, v24, v25
	v_cvt_pk_bf16_f32 v122, v26, v27
	v_cvt_pk_bf16_f32 v123, v28, v29
	v_cvt_pk_bf16_f32 v126, v30, v31
	v_cvt_pk_bf16_f32 v127, v32, v33
	v_cvt_pk_bf16_f32 v178, v34, v35
	v_cvt_pk_bf16_f32 v179, v36, v37
	v_cvt_pk_bf16_f32 v182, v38, v39
	v_cvt_pk_bf16_f32 v183, v40, v41
	v_cvt_pk_bf16_f32 v186, v42, v43
	v_cvt_pk_bf16_f32 v187, v44, v45
	v_cvt_pk_bf16_f32 v190, v46, v47
	v_cvt_pk_bf16_f32 v191, v48, v49
	v_cvt_pk_bf16_f32 v194, v50, v51
	v_cvt_pk_bf16_f32 v195, v52, v53
	v_cvt_pk_bf16_f32 v198, v54, v55
	v_cvt_pk_bf16_f32 v199, v56, v57
	v_cvt_pk_bf16_f32 v202, v58, v59
	v_cvt_pk_bf16_f32 v203, v60, v61
	v_cvt_pk_bf16_f32 v206, v62, v63
	v_cvt_pk_bf16_f32 v207, v64, v65
	v_readlane_b32 s56, v248, 13
	v_readlane_b32 s57, v248, 14
	s_mul_i32 s0, s51, 0xa000
	s_lshl_b32 s1, s2, 2
	s_add_i32 s0, s0, s1
	s_add_u32 s56, s56, s0
	s_addc_u32 s57, s57, 0
	s_mul_i32 s0, s2, 0x880
	s_add_u32 s58, s8, s0
	s_addc_u32 s59, s9, 0
	v_mov_b32_e32 v228, v224
	global_store_dwordx2 v228, v[98:99], s[58:59] sc1
	v_add_u32_e32 v228, 0x4400, v228
	global_store_dwordx2 v228, v[102:103], s[58:59] sc1
	v_add_u32_e32 v228, 0x4400, v228
	global_store_dwordx2 v228, v[106:107], s[58:59] sc1
	v_add_u32_e32 v228, 0x4400, v228
	global_store_dwordx2 v228, v[110:111], s[58:59] sc1
	v_add_u32_e32 v228, 0x4400, v228
	global_store_dwordx2 v228, v[114:115], s[58:59] sc1
	v_add_u32_e32 v228, 0x4400, v228
	global_store_dwordx2 v228, v[118:119], s[58:59] sc1
	v_add_u32_e32 v228, 0x4400, v228
	global_store_dwordx2 v228, v[122:123], s[58:59] sc1
	v_add_u32_e32 v228, 0x4400, v228
	global_store_dwordx2 v228, v[126:127], s[58:59] sc1
	v_add_u32_e32 v228, 0x4400, v228
	global_store_dwordx2 v228, v[178:179], s[58:59] sc1
	v_add_u32_e32 v228, 0x4400, v228
	global_store_dwordx2 v228, v[182:183], s[58:59] sc1
	v_add_u32_e32 v228, 0x4400, v228
	global_store_dwordx2 v228, v[186:187], s[58:59] sc1
	v_add_u32_e32 v228, 0x4400, v228
	global_store_dwordx2 v228, v[190:191], s[58:59] sc1
	v_add_u32_e32 v228, 0x4400, v228
	global_store_dwordx2 v228, v[194:195], s[58:59] sc1
	v_add_u32_e32 v228, 0x4400, v228
	global_store_dwordx2 v228, v[198:199], s[58:59] sc1
	v_add_u32_e32 v228, 0x4400, v228
	global_store_dwordx2 v228, v[202:203], s[58:59] sc1
	v_add_u32_e32 v228, 0x4400, v228
	global_store_dwordx2 v228, v[206:207], s[58:59] sc1
	v_add_f32_dpp v229, v229, v229 quad_perm:[1,0,3,2] row_mask:0xf bank_mask:0xf
	v_add_f32_dpp v230, v230, v230 quad_perm:[1,0,3,2] row_mask:0xf bank_mask:0xf
	v_add_f32_dpp v231, v231, v231 quad_perm:[1,0,3,2] row_mask:0xf bank_mask:0xf
	v_add_f32_dpp v232, v232, v232 quad_perm:[1,0,3,2] row_mask:0xf bank_mask:0xf
	v_add_f32_dpp v233, v233, v233 quad_perm:[1,0,3,2] row_mask:0xf bank_mask:0xf
	v_add_f32_dpp v234, v234, v234 quad_perm:[1,0,3,2] row_mask:0xf bank_mask:0xf
	v_add_f32_dpp v235, v235, v235 quad_perm:[1,0,3,2] row_mask:0xf bank_mask:0xf
	v_add_f32_dpp v236, v236, v236 quad_perm:[1,0,3,2] row_mask:0xf bank_mask:0xf
	v_add_f32_dpp v237, v237, v237 quad_perm:[1,0,3,2] row_mask:0xf bank_mask:0xf
	v_add_f32_dpp v238, v238, v238 quad_perm:[1,0,3,2] row_mask:0xf bank_mask:0xf
	v_add_f32_dpp v239, v239, v239 quad_perm:[1,0,3,2] row_mask:0xf bank_mask:0xf
	v_add_f32_dpp v240, v240, v240 quad_perm:[1,0,3,2] row_mask:0xf bank_mask:0xf
	v_add_f32_dpp v241, v241, v241 quad_perm:[1,0,3,2] row_mask:0xf bank_mask:0xf
	v_add_f32_dpp v242, v242, v242 quad_perm:[1,0,3,2] row_mask:0xf bank_mask:0xf
	v_add_f32_dpp v243, v243, v243 quad_perm:[1,0,3,2] row_mask:0xf bank_mask:0xf
	v_add_f32_dpp v244, v244, v244 quad_perm:[1,0,3,2] row_mask:0xf bank_mask:0xf
	v_add_f32_dpp v229, v229, v229 quad_perm:[2,3,0,1] row_mask:0xf bank_mask:0xf
	v_add_f32_dpp v230, v230, v230 quad_perm:[2,3,0,1] row_mask:0xf bank_mask:0xf
	v_add_f32_dpp v231, v231, v231 quad_perm:[2,3,0,1] row_mask:0xf bank_mask:0xf
	v_add_f32_dpp v232, v232, v232 quad_perm:[2,3,0,1] row_mask:0xf bank_mask:0xf
	v_add_f32_dpp v233, v233, v233 quad_perm:[2,3,0,1] row_mask:0xf bank_mask:0xf
	v_add_f32_dpp v234, v234, v234 quad_perm:[2,3,0,1] row_mask:0xf bank_mask:0xf
	v_add_f32_dpp v235, v235, v235 quad_perm:[2,3,0,1] row_mask:0xf bank_mask:0xf
	v_add_f32_dpp v236, v236, v236 quad_perm:[2,3,0,1] row_mask:0xf bank_mask:0xf
	v_add_f32_dpp v237, v237, v237 quad_perm:[2,3,0,1] row_mask:0xf bank_mask:0xf
	v_add_f32_dpp v238, v238, v238 quad_perm:[2,3,0,1] row_mask:0xf bank_mask:0xf
	v_add_f32_dpp v239, v239, v239 quad_perm:[2,3,0,1] row_mask:0xf bank_mask:0xf
	v_add_f32_dpp v240, v240, v240 quad_perm:[2,3,0,1] row_mask:0xf bank_mask:0xf
	v_add_f32_dpp v241, v241, v241 quad_perm:[2,3,0,1] row_mask:0xf bank_mask:0xf
	v_add_f32_dpp v242, v242, v242 quad_perm:[2,3,0,1] row_mask:0xf bank_mask:0xf
	v_add_f32_dpp v243, v243, v243 quad_perm:[2,3,0,1] row_mask:0xf bank_mask:0xf
	v_add_f32_dpp v244, v244, v244 quad_perm:[2,3,0,1] row_mask:0xf bank_mask:0xf
	v_add_f32_dpp v229, v229, v229 row_ror:4 row_mask:0xf bank_mask:0xf
	v_add_f32_dpp v230, v230, v230 row_ror:4 row_mask:0xf bank_mask:0xf
	v_add_f32_dpp v231, v231, v231 row_ror:4 row_mask:0xf bank_mask:0xf
	v_add_f32_dpp v232, v232, v232 row_ror:4 row_mask:0xf bank_mask:0xf
	v_add_f32_dpp v233, v233, v233 row_ror:4 row_mask:0xf bank_mask:0xf
	v_add_f32_dpp v234, v234, v234 row_ror:4 row_mask:0xf bank_mask:0xf
	v_add_f32_dpp v235, v235, v235 row_ror:4 row_mask:0xf bank_mask:0xf
	v_add_f32_dpp v236, v236, v236 row_ror:4 row_mask:0xf bank_mask:0xf
	v_add_f32_dpp v237, v237, v237 row_ror:4 row_mask:0xf bank_mask:0xf
	v_add_f32_dpp v238, v238, v238 row_ror:4 row_mask:0xf bank_mask:0xf
	v_add_f32_dpp v239, v239, v239 row_ror:4 row_mask:0xf bank_mask:0xf
	v_add_f32_dpp v240, v240, v240 row_ror:4 row_mask:0xf bank_mask:0xf
	v_add_f32_dpp v241, v241, v241 row_ror:4 row_mask:0xf bank_mask:0xf
	v_add_f32_dpp v242, v242, v242 row_ror:4 row_mask:0xf bank_mask:0xf
	v_add_f32_dpp v243, v243, v243 row_ror:4 row_mask:0xf bank_mask:0xf
	v_add_f32_dpp v244, v244, v244 row_ror:4 row_mask:0xf bank_mask:0xf
	v_add_f32_dpp v229, v229, v229 row_ror:8 row_mask:0xf bank_mask:0xf
	v_add_f32_dpp v230, v230, v230 row_ror:8 row_mask:0xf bank_mask:0xf
	v_add_f32_dpp v231, v231, v231 row_ror:8 row_mask:0xf bank_mask:0xf
	v_add_f32_dpp v232, v232, v232 row_ror:8 row_mask:0xf bank_mask:0xf
	v_add_f32_dpp v233, v233, v233 row_ror:8 row_mask:0xf bank_mask:0xf
	v_add_f32_dpp v234, v234, v234 row_ror:8 row_mask:0xf bank_mask:0xf
	v_add_f32_dpp v235, v235, v235 row_ror:8 row_mask:0xf bank_mask:0xf
	v_add_f32_dpp v236, v236, v236 row_ror:8 row_mask:0xf bank_mask:0xf
	v_add_f32_dpp v237, v237, v237 row_ror:8 row_mask:0xf bank_mask:0xf
	v_add_f32_dpp v238, v238, v238 row_ror:8 row_mask:0xf bank_mask:0xf
	v_add_f32_dpp v239, v239, v239 row_ror:8 row_mask:0xf bank_mask:0xf
	v_add_f32_dpp v240, v240, v240 row_ror:8 row_mask:0xf bank_mask:0xf
	v_add_f32_dpp v241, v241, v241 row_ror:8 row_mask:0xf bank_mask:0xf
	v_add_f32_dpp v242, v242, v242 row_ror:8 row_mask:0xf bank_mask:0xf
	v_add_f32_dpp v243, v243, v243 row_ror:8 row_mask:0xf bank_mask:0xf
	v_add_f32_dpp v244, v244, v244 row_ror:8 row_mask:0xf bank_mask:0xf
	v_add_f32_dpp v229, v229, v229 row_bcast:15 row_mask:0xa bank_mask:0xf
	v_add_f32_dpp v230, v230, v230 row_bcast:15 row_mask:0xa bank_mask:0xf
	v_add_f32_dpp v231, v231, v231 row_bcast:15 row_mask:0xa bank_mask:0xf
	v_add_f32_dpp v232, v232, v232 row_bcast:15 row_mask:0xa bank_mask:0xf
	v_add_f32_dpp v233, v233, v233 row_bcast:15 row_mask:0xa bank_mask:0xf
	v_add_f32_dpp v234, v234, v234 row_bcast:15 row_mask:0xa bank_mask:0xf
	v_add_f32_dpp v235, v235, v235 row_bcast:15 row_mask:0xa bank_mask:0xf
	v_add_f32_dpp v236, v236, v236 row_bcast:15 row_mask:0xa bank_mask:0xf
	v_add_f32_dpp v237, v237, v237 row_bcast:15 row_mask:0xa bank_mask:0xf
	v_add_f32_dpp v238, v238, v238 row_bcast:15 row_mask:0xa bank_mask:0xf
	v_add_f32_dpp v239, v239, v239 row_bcast:15 row_mask:0xa bank_mask:0xf
	v_add_f32_dpp v240, v240, v240 row_bcast:15 row_mask:0xa bank_mask:0xf
	v_add_f32_dpp v241, v241, v241 row_bcast:15 row_mask:0xa bank_mask:0xf
	v_add_f32_dpp v242, v242, v242 row_bcast:15 row_mask:0xa bank_mask:0xf
	v_add_f32_dpp v243, v243, v243 row_bcast:15 row_mask:0xa bank_mask:0xf
	v_add_f32_dpp v244, v244, v244 row_bcast:15 row_mask:0xa bank_mask:0xf
	s_mov_b64 s[40:41], exec
	s_mov_b32 s0, 0x80000000
	s_mov_b32 s1, 0x80000000
	s_mov_b64 exec, s[0:1]
	global_store_dword v226, v229, s[56:57]
	global_store_dword v226, v230, s[56:57] offset:32
	global_store_dword v226, v231, s[56:57] offset:64
	global_store_dword v226, v232, s[56:57] offset:96
	global_store_dword v226, v233, s[56:57] offset:128
	global_store_dword v226, v234, s[56:57] offset:160
	global_store_dword v226, v235, s[56:57] offset:192
	global_store_dword v226, v236, s[56:57] offset:224
	global_store_dword v226, v237, s[56:57] offset:256
	global_store_dword v226, v238, s[56:57] offset:288
	global_store_dword v226, v239, s[56:57] offset:320
	global_store_dword v226, v240, s[56:57] offset:352
	global_store_dword v226, v241, s[56:57] offset:384
	global_store_dword v226, v242, s[56:57] offset:416
	global_store_dword v226, v243, s[56:57] offset:448
	global_store_dword v226, v244, s[56:57] offset:480
	s_mov_b64 exec, s[40:41]
	s_branch .LBB0_122
